# v16: phase-2 gate stage: min(x,0) without the separate canonicalising max, dead zero-initialisations removed
# speedup vs baseline: 1.0085x; 1.0075x over previous
; #define LAS __attribute__((address_space(3)))
; __device__ __forceinline__ void phase_gla_pre(const Params& P, LAS unsigned char* lds, bool dry) {
;     ...
;         const int bh = item >> 6, c = item & 63, b = bh >> 2, h = bh & 3, row0 = b * SEQ + c * 64;
;         if (tid < 256) *(LAS f32x4*)(Llr + 4 * tid) = rl;
;         bf16x8 bhi = (bf16x8){0, 0, 0, 0, 0, 0, 0, 0}, blo = bhi;
;         if (g < 2) { f32x4 w0, w1;
; #pragma unroll
;             for (int j = 0; j < 4; ++j) { w0[j] = P.w_gate_up[(8 * g + j) * 512 + h * 128 + 16 * w + fr]; w1[j] = P.w_gate_up[(8 * g + 4 + j) * 512 + h * 128 + 16 * w + fr]; }
;             split8(w0, w1, bhi, blo); }
;         const float bg = P.b_gate_up[h * 128 + 16 * w + fr];
.Lp2_nopf:
	s_ashr_i32 s82, s80, 6
	s_lshl_b32 s36, s82, 7
	s_and_b32 s42, s36, 0x180
	v_mov_b32_e32 v24, 0
	v_mov_b32_e32 v25, 0
	v_mov_b32_e32 v26, 0
	v_mov_b32_e32 v27, 0
	v_mov_b32_e32 v20, 0
	v_mov_b32_e32 v21, 0
	v_mov_b32_e32 v22, 0
	v_mov_b32_e32 v23, 0
	s_cmp_lg_u32 s98, 0
	s_cbranch_scc1 .Lp2_hoisted
	s_and_saveexec_b64 s[36:37], s[6:7]
	s_cbranch_execz .LBB0_484
	v_or_b32_e32 v28, s42, v80
	v_or_b32_e32 v26, 0x400, v28
	v_add_u32_e32 v20, v28, v81
	v_add_u32_e32 v24, v26, v81
	v_add_u32_e32 v26, v26, v82
	v_or_b32_e32 v30, 0x600, v28
	v_ashrrev_i32_e32 v21, 31, v20
	v_add_u32_e32 v22, v28, v82
	v_ashrrev_i32_e32 v25, 31, v24
	v_ashrrev_i32_e32 v27, 31, v26
	v_add_u32_e32 v28, v30, v81
	v_add_u32_e32 v30, v30, v82
	v_lshl_add_u64 v[20:21], v[20:21], 2, s[54:55]
	v_ashrrev_i32_e32 v23, 31, v22
	v_lshl_add_u64 v[24:25], v[24:25], 2, s[54:55]
	v_lshl_add_u64 v[26:27], v[26:27], 2, s[54:55]
	v_ashrrev_i32_e32 v29, 31, v28
	v_ashrrev_i32_e32 v31, 31, v30
	v_lshl_add_u64 v[22:23], v[22:23], 2, s[54:55]
	v_lshl_add_u64 v[28:29], v[28:29], 2, s[54:55]
	v_lshl_add_u64 v[30:31], v[30:31], 2, s[54:55]
	global_load_dword v34, v[20:21], off
	global_load_dword v36, v[22:23], off
	global_load_dword v37, v[22:23], off offset:2048
	s_nop 0
	global_load_dword v24, v[24:25], off
	s_nop 0
	global_load_dword v26, v[26:27], off
	s_nop 0
	global_load_dword v25, v[28:29], off
	global_load_dword v27, v[30:31], off
	global_load_dword v35, v[20:21], off offset:2048
	s_waitcnt vmcnt(7)
	v_and_b32_sdwa v20, v34, v95 dst_sel:DWORD dst_unused:UNUSED_PAD src0_sel:WORD_1 src1_sel:DWORD
	s_waitcnt vmcnt(6)
	v_and_b32_sdwa v22, v36, v95 dst_sel:DWORD dst_unused:UNUSED_PAD src0_sel:WORD_1 src1_sel:DWORD
	s_waitcnt vmcnt(5)
	v_and_b32_sdwa v21, v37, v95 dst_sel:DWORD dst_unused:UNUSED_PAD src0_sel:WORD_1 src1_sel:DWORD
	v_add3_u32 v33, v34, v20, s86
	s_waitcnt vmcnt(4)
	v_and_b32_sdwa v29, v24, v95 dst_sel:DWORD dst_unused:UNUSED_PAD src0_sel:WORD_1 src1_sel:DWORD
	s_waitcnt vmcnt(2)
	v_and_b32_sdwa v20, v25, v95 dst_sel:DWORD dst_unused:UNUSED_PAD src0_sel:WORD_1 src1_sel:DWORD
	s_waitcnt vmcnt(1)
	v_and_b32_sdwa v31, v27, v95 dst_sel:DWORD dst_unused:UNUSED_PAD src0_sel:WORD_1 src1_sel:DWORD
	s_waitcnt vmcnt(0)
	v_and_b32_sdwa v23, v35, v95 dst_sel:DWORD dst_unused:UNUSED_PAD src0_sel:WORD_1 src1_sel:DWORD
	v_and_b32_sdwa v38, v26, v95 dst_sel:DWORD dst_unused:UNUSED_PAD src0_sel:WORD_1 src1_sel:DWORD
	v_add3_u32 v30, v37, v21, s86
	v_add3_u32 v22, v36, v22, s86
	v_add3_u32 v23, v35, v23, s86
	v_add3_u32 v40, v25, v20, s86
	v_add3_u32 v41, v24, v29, s86
	v_add3_u32 v42, v27, v31, s86
	v_add3_u32 v43, v26, v38, s86
	v_and_b32_e32 v28, 0xffff0000, v33
	v_and_b32_e32 v21, 0xffff0000, v30
	v_and_b32_e32 v20, 0xffff0000, v22
	v_cvt_pk_bf16_f32 v22, v36, v37
	v_and_b32_e32 v29, 0xffff0000, v23
	v_and_b32_e32 v31, 0xffff0000, v40
	v_and_b32_e32 v30, 0xffff0000, v41
	v_and_b32_e32 v39, 0xffff0000, v42
	v_and_b32_e32 v38, 0xffff0000, v43
	v_pk_add_f32 v[36:37], v[36:37], v[20:21] neg_lo:[0,1] neg_hi:[0,1]
	v_pk_add_f32 v[28:29], v[34:35], v[28:29] neg_lo:[0,1] neg_hi:[0,1]
	v_cvt_pk_bf16_f32 v137, v24, v25
	v_pk_add_f32 v[24:25], v[24:25], v[30:31] neg_lo:[0,1] neg_hi:[0,1]
	v_cvt_pk_bf16_f32 v181, v26, v27
	v_pk_add_f32 v[26:27], v[26:27], v[38:39] neg_lo:[0,1] neg_hi:[0,1]
	v_cvt_pk_bf16_f32 v20, v34, v35
	v_cvt_pk_bf16_f32 v138, v36, v37
	v_cvt_pk_bf16_f32 v180, v26, v27
	v_cvt_pk_bf16_f32 v149, v24, v25
	v_cvt_pk_bf16_f32 v139, v28, v29
	v_mov_b32_e32 v21, v137
	v_mov_b32_e32 v26, v138
	v_mov_b32_e32 v24, v139
	v_mov_b32_e32 v25, v149
	v_mov_b32_e32 v27, v180
	v_mov_b32_e32 v23, v181

; #define LAS __attribute__((address_space(3)))
; __device__ __forceinline__ void phase_gla_pre(const Params& P, LAS unsigned char* lds, bool dry) {
;     ...
;         __syncthreads();
;         float run = 0.f;
; #pragma unroll
;         for (int tt = 0; tt < 4; ++tt) {
;             bf16x8 ahi = (bf16x8){0, 0, 0, 0, 0, 0, 0, 0}, alo = ahi;
;             if (g < 2) { const f32x4 l0 = *(const LAS f32x4*)(Llr + (16 * tt + fr) * 16 + 8 * g), l1 = *(const LAS f32x4*)(Llr + (16 * tt + fr) * 16 + 8 * g + 4); split8(l0, l1, ahi, alo); }
.Lp2_join:
	s_waitcnt lgkmcnt(0)
	s_barrier
	v_mov_b32_e32 v100, 0
	v_mov_b32_e32 v101, 0
	v_mov_b32_e32 v102, 0
	v_mov_b32_e32 v103, 0
	v_mov_b32_e32 v104, 0
	v_mov_b32_e32 v105, 0
	v_mov_b32_e32 v106, 0
	v_mov_b32_e32 v107, 0
	s_and_saveexec_b64 s[36:37], s[6:7]
	s_cbranch_execz .LBB0_486
	ds_read_b128 v[30:33], v96
	ds_read_b128 v[34:37], v96 offset:16
	s_waitcnt lgkmcnt(1)
	v_cvt_pk_bf16_f32 v104, v30, v31
	v_lshlrev_b32_e32 v132, 16, v104
	v_and_b32_e32 v133, 0xffff0000, v104
	v_pk_add_f32 v[30:31], v[30:31], v[132:133] neg_lo:[0,1] neg_hi:[0,1]
	v_cvt_pk_bf16_f32 v105, v32, v33
	v_lshlrev_b32_e32 v134, 16, v105
	v_and_b32_e32 v135, 0xffff0000, v105
	v_pk_add_f32 v[32:33], v[32:33], v[134:135] neg_lo:[0,1] neg_hi:[0,1]
	s_waitcnt lgkmcnt(0)
	v_cvt_pk_bf16_f32 v106, v34, v35
	v_lshlrev_b32_e32 v136, 16, v106
	v_and_b32_e32 v137, 0xffff0000, v106
	v_pk_add_f32 v[34:35], v[34:35], v[136:137] neg_lo:[0,1] neg_hi:[0,1]
	v_cvt_pk_bf16_f32 v107, v36, v37
	v_lshlrev_b32_e32 v138, 16, v107
	v_and_b32_e32 v139, 0xffff0000, v107
	v_pk_add_f32 v[36:37], v[36:37], v[138:139] neg_lo:[0,1] neg_hi:[0,1]
	s_nop 0
	v_cvt_pk_bf16_f32 v103, v36, v37
	v_cvt_pk_bf16_f32 v102, v34, v35
	v_cvt_pk_bf16_f32 v101, v32, v33
	v_cvt_pk_bf16_f32 v100, v30, v31

; #define LAS __attribute__((address_space(3)))
; __device__ __forceinline__ void phase_gla_pre(const Params& P, LAS unsigned char* lds, bool dry) {
;     ...
;         for (int tt = 0; tt < 4; ++tt) {
;             bf16x8 ahi = (bf16x8){0, 0, 0, 0, 0, 0, 0, 0}, alo = ahi;
;             if (g < 2) { const f32x4 l0 = *(const LAS f32x4*)(Llr + (16 * tt + fr) * 16 + 8 * g), l1 = *(const LAS f32x4*)(Llr + (16 * tt + fr) * 16 + 8 * g + 4); split8(l0, l1, ahi, alo); }
;             f32x4 acc = (f32x4){bg, bg, bg, bg};
;             acc = __builtin_amdgcn_mfma_f32_16x16x32_bf16(alo, bhi, acc, 0, 0, 0); acc = __builtin_amdgcn_mfma_f32_16x16x32_bf16(ahi, blo, acc, 0, 0, 0); acc = __builtin_amdgcn_mfma_f32_16x16x32_bf16(ahi, bhi, acc, 0, 0, 0);
;             float pr[4];
; #pragma unroll
;             for (int r = 0; r < 4; ++r) { const float lg = acc[r]; const float ls = fminf(lg, 0.f) - __logf(1.0f + __expf(-fabsf(lg))); pr[r] = ls * (1.0f / 16.0f) + (r ? pr[r - 1] : 0.f); }
;             const float T = pr[3];
;             const float u1 = __shfl_up(T, 16), s1 = T + (g >= 1 ? u1 : 0.f);
;             const float u2 = __shfl_up(s1, 32), s2 = s1 + (g >= 2 ? u2 : 0.f);
;             const float base = run + (s2 - T); run += __shfl(s2, 48 + fr);
; #pragma unroll
;             for (int r = 0; r < 4; ++r) *(LAS float*)(Lb + (16 * tt + 4 * g + r) * BP + (16 * w + fr) * 4) = base + pr[r];
;         }
.Lp2_nowait1:
	v_mov_b32_e32 v140, v20
	v_mov_b32_e32 v141, v21
	v_mov_b32_e32 v142, v22
	v_mov_b32_e32 v143, v23
	v_mov_b32_e32 v144, v24
	v_mov_b32_e32 v145, v25
	v_mov_b32_e32 v146, v26
	v_mov_b32_e32 v147, v27
	v_mov_b32_e32 v148, v28
	s_and_b32 s98, s38, 0xff
	s_cselect_b32 s98, 0, 1
	v_mov_b32_e32 v29, v28
	v_mov_b32_e32 v30, v28
	v_mov_b32_e32 v31, v28
	s_nop 1
	v_mfma_f32_16x16x32_bf16 v[32:35], v[100:103], v[20:23], v[28:31]
	v_mfma_f32_16x16x32_bf16 v[32:35], v[104:107], v[24:27], v[32:35]
	v_mfma_f32_16x16x32_bf16 v[32:35], v[104:107], v[20:23], v[32:35]
	s_nop 7
	v_min_f32_e32 v36, 0, v32
	v_mul_f32_e64 v32, |v32|, s89
	v_exp_f32_e32 v32, v32
	v_mul_f32_e64 v37, |v33|, s89
	v_exp_f32_e32 v37, v37
	v_add_f32_e32 v32, 1.0, v32
	v_add_f32_e32 v37, 1.0, v37
	v_log_f32_e32 v32, v32
	v_log_f32_e32 v37, v37
	v_mul_f32_e32 v39, 0x3f317217, v32
	v_fma_f32 v39, v32, s91, -v39
	v_fmac_f32_e32 v39, 0x3377d1cf, v32
	v_fmac_f32_e32 v39, 0x3f317217, v32
	v_min_f32_e32 v33, 0, v33
	v_mov_b32_e32 v32, v39
	v_sub_f32_e32 v32, v36, v32
	v_mul_f32_e32 v36, 0x3f317217, v37
	v_fma_f32 v36, v37, s91, -v36
	v_fmac_f32_e32 v36, 0x3377d1cf, v37
	v_fmac_f32_e32 v36, 0x3f317217, v37
	v_fma_f32 v32, v32, s93, 0
	v_mul_f32_e64 v37, |v34|, s89
	v_exp_f32_e32 v37, v37
	v_sub_f32_e32 v33, v33, v36
	v_add_f32_e32 v36, 1.0, v37
	s_nop 1
	v_log_f32_e32 v36, v36
	v_fmamk_f32 v37, v33, 0x3d800000, v32
	v_min_f32_e32 v33, 0, v34
	v_mul_f32_e32 v34, 0x3f317217, v36
	v_fma_f32 v34, v36, s91, -v34
	v_fmac_f32_e32 v34, 0x3377d1cf, v36
	v_fmac_f32_e32 v34, 0x3f317217, v36
	s_nop 0
	v_mul_f32_e64 v36, |v35|, s89
	v_exp_f32_e32 v36, v36
	v_sub_f32_e32 v33, v33, v34
	v_add_u32_e32 v38, 0x8800, v98
	v_add_f32_e32 v34, 1.0, v36
	s_nop 1
	v_log_f32_e32 v34, v34
	v_fmamk_f32 v36, v33, 0x3d800000, v37
	v_min_f32_e32 v33, 0, v35
	v_mul_f32_e32 v35, 0x3f317217, v34
	v_fma_f32 v35, v34, s91, -v35
	v_fmac_f32_e32 v35, 0x3377d1cf, v34
	v_fmac_f32_e32 v35, 0x3f317217, v34
	s_nop 1
	v_mov_b32_e32 v34, v35
	v_sub_f32_e32 v33, v33, v34
	v_fmamk_f32 v34, v33, 0x3d800000, v36
	ds_bpermute_b32 v33, v83, v34
	s_waitcnt lgkmcnt(0)
	v_cndmask_b32_e64 v33, v33, 0, s[8:9]
	v_add_f32_e32 v33, v33, v34
	ds_bpermute_b32 v35, v84, v33
	s_waitcnt lgkmcnt(0)
	v_cndmask_b32_e64 v35, 0, v35, s[10:11]
	v_add_f32_e32 v33, v35, v33
	v_sub_f32_e32 v35, v33, v34
	ds_bpermute_b32 v33, v85, v33
	v_add_f32_e32 v35, 0, v35
	v_add_f32_e32 v32, v32, v35
	v_add_f32_e32 v37, v37, v35
	ds_write2_b32 v38, v32, v37 offset1:132
	v_add_f32_e32 v32, v36, v35
	v_add_f32_e32 v34, v34, v35
	v_add_u32_e32 v35, 0x8c00, v98
	ds_write2_b32 v35, v32, v34 offset0:8 offset1:140
	v_mov_b32_e32 v108, 0
	v_mov_b32_e32 v109, 0
	v_mov_b32_e32 v110, 0
	v_mov_b32_e32 v111, 0
	v_mov_b32_e32 v112, 0
	v_mov_b32_e32 v113, 0
	v_mov_b32_e32 v114, 0
	v_mov_b32_e32 v115, 0
	s_and_saveexec_b64 s[36:37], s[6:7]
	s_cbranch_execz .LBB0_488
	ds_read_b128 v[34:37], v96 offset:1024
	ds_read_b128 v[38:41], v96 offset:1040
	s_waitcnt lgkmcnt(1)
	v_cvt_pk_bf16_f32 v112, v34, v35
	v_lshlrev_b32_e32 v132, 16, v112
	v_and_b32_e32 v133, 0xffff0000, v112
	v_pk_add_f32 v[34:35], v[34:35], v[132:133] neg_lo:[0,1] neg_hi:[0,1]
	v_cvt_pk_bf16_f32 v113, v36, v37
	v_lshlrev_b32_e32 v134, 16, v113
	v_and_b32_e32 v135, 0xffff0000, v113
	v_pk_add_f32 v[36:37], v[36:37], v[134:135] neg_lo:[0,1] neg_hi:[0,1]
	s_waitcnt lgkmcnt(0)
	v_cvt_pk_bf16_f32 v114, v38, v39
	v_lshlrev_b32_e32 v136, 16, v114
	v_and_b32_e32 v137, 0xffff0000, v114
	v_pk_add_f32 v[38:39], v[38:39], v[136:137] neg_lo:[0,1] neg_hi:[0,1]
	v_cvt_pk_bf16_f32 v115, v40, v41
	v_lshlrev_b32_e32 v138, 16, v115
	v_and_b32_e32 v139, 0xffff0000, v115
	v_pk_add_f32 v[40:41], v[40:41], v[138:139] neg_lo:[0,1] neg_hi:[0,1]
	s_nop 0
	v_cvt_pk_bf16_f32 v111, v40, v41
	v_cvt_pk_bf16_f32 v110, v38, v39
	v_cvt_pk_bf16_f32 v109, v36, v37
	v_cvt_pk_bf16_f32 v108, v34, v35
.LBB0_488:
	s_or_b64 exec, exec, s[36:37]
	s_nop 0
	v_mfma_f32_16x16x32_bf16 v[34:37], v[108:111], v[20:23], v[28:31]
	v_mfma_f32_16x16x32_bf16 v[34:37], v[112:115], v[24:27], v[34:37]
	v_mfma_f32_16x16x32_bf16 v[34:37], v[112:115], v[20:23], v[34:37]
	s_nop 7
	v_min_f32_e32 v38, 0, v34
	v_mul_f32_e64 v34, |v34|, s89
	v_exp_f32_e32 v34, v34
	v_mul_f32_e64 v39, |v35|, s89
	v_exp_f32_e32 v39, v39
	v_add_f32_e32 v34, 1.0, v34
	v_add_f32_e32 v39, 1.0, v39
	v_log_f32_e32 v34, v34
	v_log_f32_e32 v39, v39
	v_mul_f32_e32 v41, 0x3f317217, v34
	v_fma_f32 v41, v34, s91, -v41
	v_fmac_f32_e32 v41, 0x3377d1cf, v34
	v_fmac_f32_e32 v41, 0x3f317217, v34
	v_mul_f32_e32 v42, 0x3f317217, v39
	v_mov_b32_e32 v34, v41
	v_sub_f32_e32 v34, v38, v34
	v_fma_f32 v38, v39, s91, -v42
	v_fmac_f32_e32 v38, 0x3377d1cf, v39
	v_fmac_f32_e32 v38, 0x3f317217, v39
	v_min_f32_e32 v35, 0, v35
	v_mul_f32_e64 v39, |v36|, s89
	v_exp_f32_e32 v39, v39
	v_sub_f32_e32 v35, v35, v38
	v_add_f32_e32 v38, 1.0, v39
	v_min_f32_e32 v36, 0, v36
	v_fma_f32 v34, v34, s93, 0
	v_log_f32_e32 v38, v38
	v_fmamk_f32 v35, v35, 0x3d800000, v34
	v_mul_f32_e32 v39, 0x3f317217, v38
	v_fma_f32 v39, v38, s91, -v39
	v_fmac_f32_e32 v39, 0x3377d1cf, v38
	v_fmac_f32_e32 v39, 0x3f317217, v38
	s_nop 1
	v_mov_b32_e32 v38, v39
	v_mul_f32_e64 v39, |v37|, s89
	v_exp_f32_e32 v39, v39
	v_sub_f32_e32 v36, v36, v38
	v_add_f32_e32 v38, 1.0, v39
	v_min_f32_e32 v37, 0, v37
	v_fmamk_f32 v36, v36, 0x3d800000, v35
	v_log_f32_e32 v38, v38
	s_waitcnt lgkmcnt(2)
	v_add_f32_e32 v40, 0, v33
	v_mul_f32_e32 v39, 0x3f317217, v38
	v_fma_f32 v39, v38, s91, -v39
	v_fmac_f32_e32 v39, 0x3377d1cf, v38
	v_fmac_f32_e32 v39, 0x3f317217, v38
	s_nop 1
	v_mov_b32_e32 v38, v39
	v_sub_f32_e32 v37, v37, v38
	v_fmamk_f32 v37, v37, 0x3d800000, v36
	ds_bpermute_b32 v38, v83, v37
	s_waitcnt lgkmcnt(0)
	v_cndmask_b32_e64 v38, v38, 0, s[8:9]
	v_add_f32_e32 v38, v38, v37
	ds_bpermute_b32 v39, v84, v38
	s_waitcnt lgkmcnt(0)
	v_cndmask_b32_e64 v33, 0, v39, s[10:11]
	v_add_f32_e32 v33, v33, v38
	v_sub_f32_e32 v38, v33, v37
	ds_bpermute_b32 v41, v85, v33
	v_add_f32_e32 v38, v40, v38
	v_add_f32_e32 v33, v34, v38
	v_add_f32_e32 v34, v35, v38
	v_add_u32_e32 v35, 0xa800, v98
	ds_write2_b32 v35, v33, v34 offset0:64 offset1:196
	v_add_f32_e32 v33, v36, v38
	v_add_f32_e32 v34, v37, v38
	v_add_u32_e32 v35, 0xac00, v98
	ds_write2_b32 v35, v33, v34 offset0:72 offset1:204
	v_mov_b32_e32 v116, 0
	v_mov_b32_e32 v117, 0
	v_mov_b32_e32 v118, 0
	v_mov_b32_e32 v119, 0
	v_mov_b32_e32 v120, 0
	v_mov_b32_e32 v121, 0
	v_mov_b32_e32 v122, 0
	v_mov_b32_e32 v123, 0
	s_and_saveexec_b64 s[36:37], s[6:7]
	s_cbranch_execz .LBB0_490
; #define LAS __attribute__((address_space(3)))
; __device__ __forceinline__ void phase_gla_pre(const Params& P, LAS unsigned char* lds, bool dry) {
;     ...
;         for (int tt = 0; tt < 4; ++tt) {
;             bf16x8 ahi = (bf16x8){0, 0, 0, 0, 0, 0, 0, 0}, alo = ahi;
;             if (g < 2) { const f32x4 l0 = *(const LAS f32x4*)(Llr + (16 * tt + fr) * 16 + 8 * g), l1 = *(const LAS f32x4*)(Llr + (16 * tt + fr) * 16 + 8 * g + 4); split8(l0, l1, ahi, alo); }
;             f32x4 acc = (f32x4){bg, bg, bg, bg};
;             acc = __builtin_amdgcn_mfma_f32_16x16x32_bf16(alo, bhi, acc, 0, 0, 0); acc = __builtin_amdgcn_mfma_f32_16x16x32_bf16(ahi, blo, acc, 0, 0, 0); acc = __builtin_amdgcn_mfma_f32_16x16x32_bf16(ahi, bhi, acc, 0, 0, 0);
;             float pr[4];
; #pragma unroll
;             for (int r = 0; r < 4; ++r) { const float lg = acc[r]; const float ls = fminf(lg, 0.f) - __logf(1.0f + __expf(-fabsf(lg))); pr[r] = ls * (1.0f / 16.0f) + (r ? pr[r - 1] : 0.f); }
;             const float T = pr[3];
;             const float u1 = __shfl_up(T, 16), s1 = T + (g >= 1 ? u1 : 0.f);
;             const float u2 = __shfl_up(s1, 32), s2 = s1 + (g >= 2 ? u2 : 0.f);
;             const float base = run + (s2 - T); run += __shfl(s2, 48 + fr);
; #pragma unroll
;             for (int r = 0; r < 4; ++r) *(LAS float*)(Lb + (16 * tt + 4 * g + r) * BP + (16 * w + fr) * 4) = base + pr[r];
;         }
	ds_read_b128 v[32:35], v96 offset:2048
	ds_read_b128 v[36:39], v96 offset:2064
	s_waitcnt lgkmcnt(1)
	v_cvt_pk_bf16_f32 v120, v32, v33
	v_lshlrev_b32_e32 v132, 16, v120
	v_and_b32_e32 v133, 0xffff0000, v120
	v_pk_add_f32 v[32:33], v[32:33], v[132:133] neg_lo:[0,1] neg_hi:[0,1]
	v_cvt_pk_bf16_f32 v121, v34, v35
	v_lshlrev_b32_e32 v134, 16, v121
	v_and_b32_e32 v135, 0xffff0000, v121
	v_pk_add_f32 v[34:35], v[34:35], v[134:135] neg_lo:[0,1] neg_hi:[0,1]
	s_waitcnt lgkmcnt(0)
	v_cvt_pk_bf16_f32 v122, v36, v37
	v_lshlrev_b32_e32 v136, 16, v122
	v_and_b32_e32 v137, 0xffff0000, v122
	v_pk_add_f32 v[36:37], v[36:37], v[136:137] neg_lo:[0,1] neg_hi:[0,1]
	v_cvt_pk_bf16_f32 v123, v38, v39
	v_lshlrev_b32_e32 v138, 16, v123
	v_and_b32_e32 v139, 0xffff0000, v123
	v_pk_add_f32 v[38:39], v[38:39], v[138:139] neg_lo:[0,1] neg_hi:[0,1]
	s_nop 0
	v_cvt_pk_bf16_f32 v119, v38, v39
	v_cvt_pk_bf16_f32 v118, v36, v37
	v_cvt_pk_bf16_f32 v117, v34, v35
	v_cvt_pk_bf16_f32 v116, v32, v33
.LBB0_490:
	s_or_b64 exec, exec, s[36:37]
	s_nop 0
	v_mfma_f32_16x16x32_bf16 v[32:35], v[116:119], v[20:23], v[28:31]
	s_waitcnt lgkmcnt(2)
	v_add_f32_e32 v40, v40, v41
	v_mfma_f32_16x16x32_bf16 v[32:35], v[120:123], v[24:27], v[32:35]
	v_mfma_f32_16x16x32_bf16 v[32:35], v[120:123], v[20:23], v[32:35]
	s_nop 7
	v_min_f32_e32 v36, 0, v32
	v_mul_f32_e64 v32, |v32|, s89
	v_exp_f32_e32 v32, v32
	v_mul_f32_e64 v37, |v33|, s89
	v_exp_f32_e32 v37, v37
	v_add_f32_e32 v32, 1.0, v32
	v_add_f32_e32 v37, 1.0, v37
	v_log_f32_e32 v32, v32
	v_log_f32_e32 v37, v37
	v_mul_f32_e32 v39, 0x3f317217, v32
	v_fma_f32 v39, v32, s91, -v39
	v_fmac_f32_e32 v39, 0x3377d1cf, v32
	v_fmac_f32_e32 v39, 0x3f317217, v32
	v_mul_f32_e32 v42, 0x3f317217, v37
	v_mov_b32_e32 v32, v39
	v_sub_f32_e32 v32, v36, v32
	v_fma_f32 v36, v37, s91, -v42
	v_fmac_f32_e32 v36, 0x3377d1cf, v37
	v_fmac_f32_e32 v36, 0x3f317217, v37
	v_min_f32_e32 v33, 0, v33
	v_mul_f32_e64 v37, |v34|, s89
	v_exp_f32_e32 v37, v37
	v_sub_f32_e32 v33, v33, v36
	v_add_f32_e32 v36, 1.0, v37
	v_min_f32_e32 v34, 0, v34
	v_fma_f32 v32, v32, s93, 0
	v_log_f32_e32 v36, v36
	v_fmamk_f32 v33, v33, 0x3d800000, v32
	v_mul_f32_e32 v37, 0x3f317217, v36
	v_fma_f32 v37, v36, s91, -v37
	v_fmac_f32_e32 v37, 0x3377d1cf, v36
	v_fmac_f32_e32 v37, 0x3f317217, v36
	s_nop 1
	v_mov_b32_e32 v36, v37
	v_mul_f32_e64 v37, |v35|, s89
	v_exp_f32_e32 v37, v37
	v_sub_f32_e32 v34, v34, v36
	v_add_f32_e32 v36, 1.0, v37
	v_min_f32_e32 v35, 0, v35
	v_fmamk_f32 v34, v34, 0x3d800000, v33
	v_log_f32_e32 v36, v36
	s_nop 0
	v_mul_f32_e32 v37, 0x3f317217, v36
	v_fma_f32 v37, v36, s91, -v37
	v_fmac_f32_e32 v37, 0x3377d1cf, v36
	v_fmac_f32_e32 v37, 0x3f317217, v36
	s_nop 1
	v_mov_b32_e32 v36, v37
	v_sub_f32_e32 v35, v35, v36
	v_fmamk_f32 v35, v35, 0x3d800000, v34
	ds_bpermute_b32 v36, v83, v35
	s_waitcnt lgkmcnt(0)
	v_cndmask_b32_e64 v36, v36, 0, s[8:9]
	v_add_f32_e32 v36, v36, v35
	ds_bpermute_b32 v37, v84, v36
	s_waitcnt lgkmcnt(0)
	v_cndmask_b32_e64 v37, 0, v37, s[10:11]
	v_add_f32_e32 v36, v37, v36
	v_sub_f32_e32 v37, v36, v35
	ds_bpermute_b32 v41, v85, v36
	v_add_f32_e32 v37, v40, v37
	v_add_f32_e32 v32, v32, v37
	v_add_f32_e32 v33, v33, v37
	v_add_u32_e32 v36, 0xca00, v98
	ds_write2_b32 v36, v32, v33 offset1:132
	v_add_f32_e32 v32, v34, v37
	v_add_f32_e32 v33, v35, v37
	v_add_u32_e32 v34, 0xce00, v98
	ds_write2_b32 v34, v32, v33 offset0:8 offset1:140
	v_mov_b32_e32 v124, 0
	v_mov_b32_e32 v125, 0
	v_mov_b32_e32 v126, 0
	v_mov_b32_e32 v127, 0
	v_mov_b32_e32 v128, 0
	v_mov_b32_e32 v129, 0
	v_mov_b32_e32 v130, 0
	v_mov_b32_e32 v131, 0
	s_and_saveexec_b64 s[36:37], s[6:7]
	s_cbranch_execz .LBB0_492
	ds_read_b128 v[32:35], v96 offset:3072
	ds_read_b128 v[36:39], v96 offset:3088
	s_waitcnt lgkmcnt(1)
	v_cvt_pk_bf16_f32 v128, v32, v33
	v_lshlrev_b32_e32 v132, 16, v128
	v_and_b32_e32 v133, 0xffff0000, v128
	v_pk_add_f32 v[32:33], v[32:33], v[132:133] neg_lo:[0,1] neg_hi:[0,1]
	v_cvt_pk_bf16_f32 v129, v34, v35
	v_lshlrev_b32_e32 v134, 16, v129
	v_and_b32_e32 v135, 0xffff0000, v129
	v_pk_add_f32 v[34:35], v[34:35], v[134:135] neg_lo:[0,1] neg_hi:[0,1]
	s_waitcnt lgkmcnt(0)
	v_cvt_pk_bf16_f32 v130, v36, v37
	v_lshlrev_b32_e32 v136, 16, v130
	v_and_b32_e32 v137, 0xffff0000, v130
	v_pk_add_f32 v[36:37], v[36:37], v[136:137] neg_lo:[0,1] neg_hi:[0,1]
	v_cvt_pk_bf16_f32 v131, v38, v39
	v_lshlrev_b32_e32 v138, 16, v131
	v_and_b32_e32 v139, 0xffff0000, v131
	v_pk_add_f32 v[38:39], v[38:39], v[138:139] neg_lo:[0,1] neg_hi:[0,1]
	s_nop 0
	v_cvt_pk_bf16_f32 v127, v38, v39
	v_cvt_pk_bf16_f32 v126, v36, v37
	v_cvt_pk_bf16_f32 v125, v34, v35
	v_cvt_pk_bf16_f32 v124, v32, v33
; #define LAS __attribute__((address_space(3)))
; __device__ __forceinline__ void phase_gla_pre(const Params& P, LAS unsigned char* lds, bool dry) {
;     ...
;         for (int tt = 0; tt < 4; ++tt) {
;             bf16x8 ahi = (bf16x8){0, 0, 0, 0, 0, 0, 0, 0}, alo = ahi;
;             if (g < 2) { const f32x4 l0 = *(const LAS f32x4*)(Llr + (16 * tt + fr) * 16 + 8 * g), l1 = *(const LAS f32x4*)(Llr + (16 * tt + fr) * 16 + 8 * g + 4); split8(l0, l1, ahi, alo); }
;             f32x4 acc = (f32x4){bg, bg, bg, bg};
;             acc = __builtin_amdgcn_mfma_f32_16x16x32_bf16(alo, bhi, acc, 0, 0, 0); acc = __builtin_amdgcn_mfma_f32_16x16x32_bf16(ahi, blo, acc, 0, 0, 0); acc = __builtin_amdgcn_mfma_f32_16x16x32_bf16(ahi, bhi, acc, 0, 0, 0);
;             float pr[4];
; #pragma unroll
;             for (int r = 0; r < 4; ++r) { const float lg = acc[r]; const float ls = fminf(lg, 0.f) - __logf(1.0f + __expf(-fabsf(lg))); pr[r] = ls * (1.0f / 16.0f) + (r ? pr[r - 1] : 0.f); }
;             const float T = pr[3];
;             const float u1 = __shfl_up(T, 16), s1 = T + (g >= 1 ? u1 : 0.f);
;             const float u2 = __shfl_up(s1, 32), s2 = s1 + (g >= 2 ? u2 : 0.f);
;             const float base = run + (s2 - T); run += __shfl(s2, 48 + fr);
; #pragma unroll
;             for (int r = 0; r < 4; ++r) *(LAS float*)(Lb + (16 * tt + 4 * g + r) * BP + (16 * w + fr) * 4) = base + pr[r];
;         }
;         __syncthreads();
;         {
;             f32x4 bb[4], bm[4], bl[4];
; #pragma unroll
;             for (int i = 0; i < 4; ++i) { bb[i] = *(const LAS f32x4*)(Lb + te * BP + (16 * kc + 4 * i) * 4); bm[i] = *(const LAS f32x4*)(Lb + 31 * BP + (16 * kc + 4 * i) * 4); bl[i] = *(const LAS f32x4*)(Lb + 63 * BP + (16 * kc + 4 * i) * 4); }
;             unsigned oqi[8], oki[8], oqd[8], oks[8];
; #pragma unroll
;             for (int e2 = 0; e2 < 8; ++e2) {
;                 const unsigned qw = e2 < 4 ? rq[0][e2] : rq[1][e2 - 4], kw = e2 < 4 ? rk[0][e2] : rk[1][e2 - 4];
;                 float vqi[2], vki[2], vqd[2], vks[2];
; #pragma unroll
;                 for (int hh = 0; hh < 2; ++hh) {
;                     const int e = 2 * e2 + hh; const float bv = bb[e >> 2][e & 3], bmv = bm[e >> 2][e & 3], blv = bl[e >> 2][e & 3];
;                     const float qv = hh ? bfhi(qw) : bflo(qw), kv = hh ? bfhi(kw) : bflo(kw);
;                     const float e1 = __expf(bv - bmv);
.LBB0_492:
	s_or_b64 exec, exec, s[36:37]
	s_nop 0
	v_mfma_f32_16x16x32_bf16 v[28:31], v[124:127], v[20:23], v[28:31]
	v_and_b32_e32 v111, 0xffff0000, v5
	v_and_b32_e32 v110, 0xffff0000, v4
	v_and_b32_e32 v117, 0xffff0000, v13
	v_mfma_f32_16x16x32_bf16 v[24:27], v[128:131], v[24:27], v[28:31]
	v_and_b32_e32 v116, 0xffff0000, v12
	v_and_b32_e32 v121, 0xffff0000, v7
	v_and_b32_e32 v120, 0xffff0000, v6
	v_mfma_f32_16x16x32_bf16 v[20:23], v[128:131], v[20:23], v[24:27]
	v_and_b32_e32 v127, 0xffff0000, v17
	v_and_b32_e32 v126, 0xffff0000, v16
	v_lshlrev_b32_e32 v125, 16, v17
	v_lshlrev_b32_e32 v124, 16, v16
	v_lshlrev_b32_e32 v133, 16, v11
	s_nop 2
	v_min_f32_e32 v24, 0, v20
	v_mul_f32_e64 v20, |v20|, s89
	v_exp_f32_e32 v20, v20
	v_mul_f32_e64 v25, |v21|, s89
	v_exp_f32_e32 v25, v25
	v_add_f32_e32 v20, 1.0, v20
	v_add_f32_e32 v25, 1.0, v25
	v_log_f32_e32 v20, v20
	v_log_f32_e32 v25, v25
	v_mul_f32_e32 v27, 0x3f317217, v20
	v_fma_f32 v27, v20, s91, -v27
	v_fmac_f32_e32 v27, 0x3377d1cf, v20
	v_fmac_f32_e32 v27, 0x3f317217, v20
	v_mul_f32_e32 v28, 0x3f317217, v25
	v_mov_b32_e32 v20, v27
	v_sub_f32_e32 v20, v24, v20
	v_fma_f32 v24, v25, s91, -v28
	v_fmac_f32_e32 v24, 0x3377d1cf, v25
	v_fmac_f32_e32 v24, 0x3f317217, v25
	v_min_f32_e32 v21, 0, v21
	v_mul_f32_e64 v25, |v22|, s89
	v_exp_f32_e32 v25, v25
	v_sub_f32_e32 v21, v21, v24
	v_add_f32_e32 v24, 1.0, v25
	v_min_f32_e32 v22, 0, v22
	v_fma_f32 v20, v20, s93, 0
	v_log_f32_e32 v24, v24
	v_fmamk_f32 v21, v21, 0x3d800000, v20
	v_lshlrev_b32_e32 v132, 16, v10
	v_mul_f32_e32 v25, 0x3f317217, v24
	v_fma_f32 v25, v24, s91, -v25
	v_fmac_f32_e32 v25, 0x3377d1cf, v24
	v_fmac_f32_e32 v25, 0x3f317217, v24
	v_and_b32_e32 v135, 0xffff0000, v11
	v_and_b32_e32 v134, 0xffff0000, v10
	v_mov_b32_e32 v24, v25
	v_mul_f32_e64 v25, |v23|, s89
	v_exp_f32_e32 v25, v25
	v_sub_f32_e32 v22, v22, v24
	v_add_f32_e32 v24, 1.0, v25
	v_min_f32_e32 v23, 0, v23
	v_fmamk_f32 v22, v22, 0x3d800000, v21
	v_log_f32_e32 v24, v24
	s_waitcnt lgkmcnt(2)
	v_add_f32_e32 v26, v40, v41
	s_and_b32 s74, s1, 0xfc0
	s_ashr_i32 s83, s82, 31
	v_mul_f32_e32 v25, 0x3f317217, v24
	v_fma_f32 v25, v24, s91, -v25
	v_fmac_f32_e32 v25, 0x3377d1cf, v24
	v_fmac_f32_e32 v25, 0x3f317217, v24
	s_nop 1
	v_mov_b32_e32 v24, v25
	v_sub_f32_e32 v23, v23, v24
	v_fmamk_f32 v23, v23, 0x3d800000, v22
	ds_bpermute_b32 v24, v83, v23
	s_lshl_b64 s[36:37], s[82:83], 20
	s_waitcnt lgkmcnt(0)
	v_cndmask_b32_e64 v24, v24, 0, s[8:9]
	v_add_f32_e32 v24, v24, v23
	ds_bpermute_b32 v25, v84, v24
	s_waitcnt lgkmcnt(0)
	v_cndmask_b32_e64 v25, 0, v25, s[10:11]
	v_add_f32_e32 v24, v25, v24
	v_sub_f32_e32 v24, v24, v23
	v_add_f32_e32 v24, v26, v24
	v_add_f32_e32 v20, v20, v24
	v_add_f32_e32 v21, v21, v24
	v_add_u32_e32 v25, 0xea00, v98
	ds_write2_b32 v25, v20, v21 offset0:64 offset1:196
	v_add_f32_e32 v20, v22, v24
	v_add_f32_e32 v21, v23, v24
	v_add_u32_e32 v22, 0xee00, v98
	ds_write2_b32 v22, v20, v21 offset0:72 offset1:204
	v_add_u32_e32 v22, s94, v87
	s_waitcnt lgkmcnt(0)
	s_barrier
	v_add_u32_e32 v20, v86, v87
	v_add_u32_e32 v21, 0, v87
	ds_read_b128 v[32:35], v22
	ds_read_b128 v[24:27], v89
	ds_read_b128 v[60:63], v21 offset:51184
	ds_read_b128 v[64:67], v20 offset:34816
	ds_read_b128 v[74:77], v20 offset:34832
	ds_read_b128 v[44:47], v20 offset:34848
	ds_read_b128 v[36:39], v20 offset:34864
	ds_read_b128 v[100:103], v21 offset:51200
	s_waitcnt lgkmcnt(4)
	v_sub_f32_e32 v61, v65, v61
	v_mul_f32_e32 v61, 0x3fb8aa3b, v61
	v_sub_f32_e32 v63, v67, v63
	v_exp_f32_e32 v72, v61
	v_sub_f32_e32 v61, v32, v64
	v_mul_f32_e32 v63, 0x3fb8aa3b, v63
	v_mul_f32_e32 v61, 0x3fb8aa3b, v61
	v_exp_f32_e32 v73, v63
	v_exp_f32_e32 v78, v61
	v_mul_f32_e32 v61, 0x3fb8aa3b, v65
	v_sub_f32_e32 v20, v64, v60
	v_exp_f32_e32 v108, v61
	v_sub_f32_e32 v61, v66, v62
	v_mul_f32_e32 v20, 0x3fb8aa3b, v20
	v_mul_f32_e32 v69, 0x3fb8aa3b, v64
	v_mul_f32_e32 v61, 0x3fb8aa3b, v61
	v_sub_f32_e32 v62, v33, v65
	v_mul_f32_e32 v65, 0x3fb8aa3b, v66
	v_sub_f32_e32 v63, v34, v66
	v_exp_f32_e32 v60, v20
	v_exp_f32_e32 v70, v69
	v_rcp_f32_e32 v64, v72
	v_exp_f32_e32 v61, v61
	v_exp_f32_e32 v71, v65
	v_mul_f32_e32 v63, 0x3fb8aa3b, v63
	v_rcp_f32_e32 v65, v73
	v_exp_f32_e32 v79, v63
	v_mul_f32_e32 v63, 0x3fb8aa3b, v67
	v_exp_f32_e32 v109, v63
	v_sub_f32_e32 v63, v35, v67
	v_lshlrev_b32_e32 v67, 16, v5
	v_lshlrev_b32_e32 v66, 16, v4
	v_pk_mul_f32 v[112:113], v[60:61], v[66:67]
	v_pk_mul_f32 v[114:115], v[72:73], v[110:111]
	v_pk_mul_f32 v[72:73], v[64:65], v[116:117]
	v_pk_mul_f32 v[64:65], v[70:71], v[66:67]
	s_waitcnt lgkmcnt(0)
	v_sub_f32_e32 v66, v74, v100
	v_mul_f32_e32 v66, 0x3fb8aa3b, v66
	v_mul_f32_e32 v71, 0x3fb8aa3b, v74
	v_exp_f32_e32 v70, v66
	v_pk_mul_f32 v[66:67], v[108:109], v[110:111]
	v_exp_f32_e32 v108, v71
	v_sub_f32_e32 v71, v75, v101
	v_mul_f32_e32 v71, 0x3fb8aa3b, v71
	v_mul_f32_e32 v62, 0x3fb8aa3b, v62
	v_mul_f32_e32 v63, 0x3fb8aa3b, v63
	v_exp_f32_e32 v100, v71
	v_sub_f32_e32 v71, v24, v74
	v_exp_f32_e32 v62, v62
	v_exp_f32_e32 v63, v63
	v_mul_f32_e32 v71, 0x3fb8aa3b, v71
	v_exp_f32_e32 v74, v71
	v_mul_f32_e32 v71, 0x3fb8aa3b, v75
	v_sub_f32_e32 v75, v25, v75
	v_mul_f32_e32 v75, 0x3fb8aa3b, v75
	v_exp_f32_e32 v118, v75
	v_mul_f32_e32 v75, 0x3fb8aa3b, v76
	v_pk_mul_f32 v[62:63], v[62:63], v[116:117]
	v_exp_f32_e32 v116, v71
	v_sub_f32_e32 v71, v76, v102
	v_exp_f32_e32 v109, v75
	v_sub_f32_e32 v75, v77, v103
	v_mul_f32_e32 v71, 0x3fb8aa3b, v71
	v_mul_f32_e32 v75, 0x3fb8aa3b, v75
	v_rcp_f32_e32 v68, v60
	v_rcp_f32_e32 v69, v61
	v_exp_f32_e32 v71, v71
	v_exp_f32_e32 v101, v75
	v_sub_f32_e32 v75, v26, v76
	v_mul_f32_e32 v76, 0x3fb8aa3b, v77
	v_exp_f32_e32 v117, v76
	v_sub_f32_e32 v76, v27, v77
	v_mul_f32_e32 v76, 0x3fb8aa3b, v76
	v_lshlrev_b32_e32 v61, 16, v13
	v_lshlrev_b32_e32 v60, 16, v12
	v_exp_f32_e32 v119, v76
	v_lshlrev_b32_e32 v77, 16, v7
	v_lshlrev_b32_e32 v76, 16, v6
	v_pk_mul_f32 v[68:69], v[68:69], v[60:61]
	v_pk_mul_f32 v[60:61], v[78:79], v[60:61]
	v_rcp_f32_e32 v78, v70
	v_rcp_f32_e32 v110, v100
	v_rcp_f32_e32 v79, v71
	v_rcp_f32_e32 v111, v101
	v_pk_mul_f32 v[70:71], v[70:71], v[76:77]
	v_pk_mul_f32 v[100:101], v[100:101], v[120:121]
	v_cvt_pk_bf16_f32 v224, v112, v114
	v_cvt_pk_bf16_f32 v222, v113, v115
	v_cvt_pk_bf16_f32 v221, v70, v100
	v_cvt_pk_bf16_f32 v220, v71, v101
	ds_read_b128 v[104:107], v21 offset:51216
	ds_read_b128 v[40:43], v21 offset:51232
	ds_read_b128 v[28:31], v90
	ds_read_b128 v[20:23], v91
	v_mov_b32_e32 v103, v220
	v_mov_b32_e32 v102, v221
	v_lshlrev_b32_e32 v71, 16, v15
	v_lshlrev_b32_e32 v70, 16, v14
	v_mul_f32_e32 v75, 0x3fb8aa3b, v75
	v_mov_b32_e32 v101, v222
	v_mov_b32_e32 v100, v224
	v_pk_mul_f32 v[114:115], v[78:79], v[70:71]
	s_waitcnt lgkmcnt(3)
; #define LAS __attribute__((address_space(3)))
; __device__ __forceinline__ float bflo(unsigned w) { return __uint_as_float(w << 16); }
; __device__ __forceinline__ float bfhi(unsigned w) { return __uint_as_float(w & 0xffff0000u); }
; __device__ __forceinline__ unsigned pk2(float lo, float hi) { return f2bf(lo) | (f2bf(hi) << 16); }
; __device__ __forceinline__ void phase_gla_pre(const Params& P, LAS unsigned char* lds, bool dry) {
;     ...
;             for (int e2 = 0; e2 < 8; ++e2) {
;                 const unsigned qw = e2 < 4 ? rq[0][e2] : rq[1][e2 - 4], kw = e2 < 4 ? rk[0][e2] : rk[1][e2 - 4];
;                 float vqi[2], vki[2], vqd[2], vks[2];
; #pragma unroll
;                 for (int hh = 0; hh < 2; ++hh) {
;                     const int e = 2 * e2 + hh; const float bv = bb[e >> 2][e & 3], bmv = bm[e >> 2][e & 3], blv = bl[e >> 2][e & 3];
;                     const float qv = hh ? bfhi(qw) : bflo(qw), kv = hh ? bfhi(kw) : bflo(kw);
;                     const float e1 = __expf(bv - bmv);
;                     vqi[hh] = qv * e1; vki[hh] = kv * __builtin_amdgcn_rcpf(e1); vqd[hh] = qv * __expf(bv); vks[hh] = kv * __expf(blv - bv);
;                 }
;                 oqi[e2] = pk2(vqi[0], vqi[1]); oki[e2] = pk2(vki[0], vki[1]); oqd[e2] = pk2(vqd[0], vqd[1]); oks[e2] = pk2(vks[0], vks[1]);
;             }
;             *(LAS u32x4*)(Lqi + te * QP + 32 * kc) = (u32x4){oqi[0], oqi[1], oqi[2], oqi[3]}; *(LAS u32x4*)(Lqi + te * QP + 32 * kc + 16) = (u32x4){oqi[4], oqi[5], oqi[6], oqi[7]};
;             *(LAS u32x4*)(Lki + te * QP + 32 * kc) = (u32x4){oki[0], oki[1], oki[2], oki[3]}; *(LAS u32x4*)(Lki + te * QP + 32 * kc + 16) = (u32x4){oki[4], oki[5], oki[6], oki[7]};
;             if (!dry) {
;                 bf16_t* p_ = PJ + ((size_t)bh * SEQ + c * 64 + te) * 128 + 16 * kc;
;                 *(u32x4*)(p_ + T_Q) = (u32x4){oqd[0], oqd[1], oqd[2], oqd[3]}; *(u32x4*)(p_ + T_Q + 8) = (u32x4){oqd[4], oqd[5], oqd[6], oqd[7]};
;                 *(u32x4*)(p_ + T_K) = (u32x4){oks[0], oks[1], oks[2], oks[3]}; *(u32x4*)(p_ + T_K + 8) = (u32x4){oks[4], oks[5], oks[6], oks[7]};
;                 if (te == 63) {
; #pragma unroll
;                     for (int i = 0; i < 4; ++i) *(f32x4*)(DEC + (size_t)item * 128 + 16 * kc + 4 * i) = (f32x4){__expf(bl[i][0]), __expf(bl[i][1]), __expf(bl[i][2]), __expf(bl[i][3])};
;                 }
	v_sub_f32_e32 v78, v44, v104
	v_sub_f32_e32 v105, v45, v105
	v_exp_f32_e32 v75, v75
	v_mul_f32_e32 v78, 0x3fb8aa3b, v78
	v_mul_f32_e32 v105, 0x3fb8aa3b, v105
	v_exp_f32_e32 v104, v78
	v_pk_mul_f32 v[78:79], v[116:117], v[120:121]
	v_exp_f32_e32 v116, v105
	v_mul_f32_e32 v105, 0x3fb8aa3b, v45
	s_waitcnt lgkmcnt(1)
	v_sub_f32_e32 v45, v29, v45
	v_mul_f32_e32 v45, 0x3fb8aa3b, v45
	v_and_b32_e32 v113, 0xffff0000, v15
	v_and_b32_e32 v112, 0xffff0000, v14
	v_exp_f32_e32 v120, v105
	v_sub_f32_e32 v105, v46, v106
	v_exp_f32_e32 v106, v45
	v_mul_f32_e32 v45, 0x3fb8aa3b, v46
	v_pk_mul_f32 v[110:111], v[110:111], v[112:113]
	v_pk_mul_f32 v[70:71], v[74:75], v[70:71]
	v_pk_mul_f32 v[74:75], v[118:119], v[112:113]
	v_exp_f32_e32 v113, v45
	v_sub_f32_e32 v45, v47, v107
	v_mul_f32_e32 v45, 0x3fb8aa3b, v45
	v_exp_f32_e32 v117, v45
	v_sub_f32_e32 v45, v30, v46
	v_mul_f32_e32 v46, 0x3fb8aa3b, v47
	v_exp_f32_e32 v121, v46
	v_sub_f32_e32 v46, v31, v47
	v_pk_mul_f32 v[76:77], v[108:109], v[76:77]
	v_mul_f32_e32 v109, 0x3fb8aa3b, v44
	v_mul_f32_e32 v105, 0x3fb8aa3b, v105
	v_mul_f32_e32 v46, 0x3fb8aa3b, v46
	v_exp_f32_e32 v112, v109
	v_exp_f32_e32 v105, v105
	v_exp_f32_e32 v107, v46
	v_rcp_f32_e32 v118, v116
	v_rcp_f32_e32 v119, v117
	v_sub_f32_e32 v44, v28, v44
	v_lshlrev_b32_e32 v47, 16, v9
	v_lshlrev_b32_e32 v46, 16, v8
	v_rcp_f32_e32 v108, v104
	v_mul_f32_e32 v44, 0x3fb8aa3b, v44
	v_rcp_f32_e32 v109, v105
	v_mul_f32_e32 v45, 0x3fb8aa3b, v45
	v_pk_mul_f32 v[104:105], v[104:105], v[46:47]
	v_pk_mul_f32 v[112:113], v[112:113], v[46:47]
	v_sub_f32_e32 v40, v36, v40
	v_pk_mul_f32 v[46:47], v[106:107], v[126:127]
	v_mul_f32_e32 v107, 0x3fb8aa3b, v36
	s_waitcnt lgkmcnt(0)
	v_sub_f32_e32 v36, v20, v36
	v_exp_f32_e32 v44, v44
	v_exp_f32_e32 v45, v45
	v_mul_f32_e32 v36, 0x3fb8aa3b, v36
	v_pk_mul_f32 v[118:119], v[118:119], v[126:127]
	v_exp_f32_e32 v126, v36
	v_mul_f32_e32 v36, 0x3fb8aa3b, v37
	v_sub_f32_e32 v41, v37, v41
	v_exp_f32_e32 v130, v36
	v_sub_f32_e32 v36, v38, v42
	v_mul_f32_e32 v41, 0x3fb8aa3b, v41
	v_mul_f32_e32 v36, 0x3fb8aa3b, v36
	v_pk_mul_f32 v[108:109], v[108:109], v[124:125]
	v_pk_mul_f32 v[44:45], v[44:45], v[124:125]
	v_exp_f32_e32 v124, v41
	v_exp_f32_e32 v41, v36
	v_sub_f32_e32 v36, v21, v37
	v_mul_f32_e32 v36, 0x3fb8aa3b, v36
	v_and_b32_e32 v123, 0xffff0000, v9
	v_and_b32_e32 v122, 0xffff0000, v8
	v_exp_f32_e32 v42, v36
	v_mul_f32_e32 v36, 0x3fb8aa3b, v38
	v_pk_mul_f32 v[116:117], v[116:117], v[122:123]
	v_pk_mul_f32 v[120:121], v[120:121], v[122:123]
	v_exp_f32_e32 v123, v36
	v_sub_f32_e32 v36, v39, v43
	v_mul_f32_e32 v36, 0x3fb8aa3b, v36
	v_mul_f32_e32 v40, 0x3fb8aa3b, v40
	v_exp_f32_e32 v125, v36
	v_sub_f32_e32 v36, v22, v38
	v_exp_f32_e32 v40, v40
	v_mul_f32_e32 v36, 0x3fb8aa3b, v36
	v_exp_f32_e32 v127, v36
	v_mul_f32_e32 v36, 0x3fb8aa3b, v39
	v_exp_f32_e32 v131, v36
	v_sub_f32_e32 v36, v23, v39
	v_mul_f32_e32 v36, 0x3fb8aa3b, v36
	v_rcp_f32_e32 v128, v124
	v_rcp_f32_e32 v129, v125
	v_exp_f32_e32 v43, v36
	v_pk_mul_f32 v[36:37], v[40:41], v[132:133]
	v_pk_mul_f32 v[38:39], v[124:125], v[134:135]
	v_rcp_f32_e32 v106, v40
	v_exp_f32_e32 v122, v107
	v_rcp_f32_e32 v107, v41
	v_cvt_pk_bf16_f32 v228, v104, v116
	v_cvt_pk_bf16_f32 v227, v105, v117
	v_cvt_pk_bf16_f32 v226, v36, v38
	v_cvt_pk_bf16_f32 v225, v37, v39
	v_mov_b32_e32 v39, v225
	v_mov_b32_e32 v38, v226
	v_mov_b32_e32 v37, v227
	v_mov_b32_e32 v36, v228
	ds_write_b128 v92, v[100:103]
	ds_write_b128 v92, v[36:39] offset:16
	v_cvt_pk_bf16_f32 v230, v68, v72
	v_cvt_pk_bf16_f32 v229, v69, v73
	v_lshlrev_b32_e32 v41, 16, v19
	v_lshlrev_b32_e32 v40, 16, v18
	v_cvt_pk_bf16_f32 v39, v115, v111
	v_cvt_pk_bf16_f32 v38, v114, v110
	v_mov_b32_e32 v37, v229
	v_mov_b32_e32 v36, v230
	v_and_b32_e32 v105, 0xffff0000, v19
	v_and_b32_e32 v104, 0xffff0000, v18
	v_pk_mul_f32 v[106:107], v[106:107], v[40:41]
	ds_write_b128 v92, v[36:39] offset:17408
	v_pk_mul_f32 v[116:117], v[128:129], v[104:105]
	s_nop 0
	v_cvt_pk_bf16_f32 v39, v107, v117
	v_cvt_pk_bf16_f32 v38, v106, v116
	v_cvt_pk_bf16_f32 v37, v109, v119
	v_cvt_pk_bf16_f32 v36, v108, v118
	ds_write_b128 v92, v[36:39] offset:17424
	v_lshl_add_u64 v[36:37], s[74:75], 0, v[48:49]
	v_lshlrev_b64 v[36:37], 8, v[36:37]
	v_lshl_add_u64 v[38:39], v[52:53], 0, s[36:37]
	v_lshl_add_u64 v[68:69], v[38:39], 0, v[36:37]
	v_cvt_pk_bf16_f32 v232, v64, v66
	v_cvt_pk_bf16_f32 v233, v65, v67
	s_brev_b32 s36, 16
	v_cvt_pk_bf16_f32 v39, v77, v79
	v_mov_b32_e32 v36, v232
	v_add_co_u32_e32 v64, vcc, s36, v68
	v_cvt_pk_bf16_f32 v38, v76, v78
	v_mov_b32_e32 v37, v233
	v_addc_co_u32_e32 v65, vcc, 0, v69, vcc
	v_pk_mul_f32 v[122:123], v[122:123], v[132:133]
	global_store_dwordx4 v[64:65], v[36:39], off
	v_pk_mul_f32 v[124:125], v[130:131], v[134:135]
	s_nop 0
	v_cvt_pk_bf16_f32 v39, v123, v125
	v_cvt_pk_bf16_f32 v38, v122, v124
	v_cvt_pk_bf16_f32 v37, v113, v121
	v_cvt_pk_bf16_f32 v36, v112, v120
	global_store_dwordx4 v[64:65], v[36:39], off offset:16
	s_nop 1
	s_nop 0
	v_cvt_pk_bf16_f32 v234, v60, v62
	v_cvt_pk_bf16_f32 v235, v61, v63
	v_cvt_pk_bf16_f32 v39, v71, v75
	v_mov_b32_e32 v36, v234
	v_add_co_u32_e32 v60, vcc, s95, v68
	v_pk_mul_f32 v[42:43], v[42:43], v[104:105]
	v_cvt_pk_bf16_f32 v38, v70, v74
	v_mov_b32_e32 v37, v235
	v_addc_co_u32_e32 v61, vcc, 0, v69, vcc
	v_pk_mul_f32 v[40:41], v[126:127], v[40:41]
	global_store_dwordx4 v[60:61], v[36:39], off
	s_nop 1
	v_cvt_pk_bf16_f32 v240, v44, v46
	v_cvt_pk_bf16_f32 v239, v45, v47
	v_cvt_pk_bf16_f32 v238, v40, v42
	v_cvt_pk_bf16_f32 v237, v41, v43
	v_mov_b32_e32 v39, v237
	v_mov_b32_e32 v38, v238
	v_mov_b32_e32 v37, v239
	v_mov_b32_e32 v36, v240
	global_store_dwordx4 v[60:61], v[36:39], off offset:16
	s_and_saveexec_b64 s[36:37], s[12:13]
	s_cbranch_execz .LBB0_494
	v_mul_f32_e32 v32, 0x3fb8aa3b, v32
	v_mul_f32_e32 v33, 0x3fb8aa3b, v33
	v_mul_f32_e32 v34, 0x3fb8aa3b, v34
	v_mul_f32_e32 v35, 0x3fb8aa3b, v35
	v_exp_f32_e32 v32, v32
	v_exp_f32_e32 v33, v33
	v_exp_f32_e32 v34, v34
	v_exp_f32_e32 v35, v35
	v_mul_f32_e32 v24, 0x3fb8aa3b, v24
	v_mul_f32_e32 v25, 0x3fb8aa3b, v25
	v_mul_f32_e32 v26, 0x3fb8aa3b, v26
	v_mul_f32_e32 v27, 0x3fb8aa3b, v27
	s_ashr_i32 s81, s80, 31
	v_exp_f32_e32 v24, v24
	v_exp_f32_e32 v25, v25
	v_exp_f32_e32 v26, v26
	v_exp_f32_e32 v27, v27
	v_mul_f32_e32 v28, 0x3fb8aa3b, v28
	v_mul_f32_e32 v29, 0x3fb8aa3b, v29
	v_mul_f32_e32 v30, 0x3fb8aa3b, v30
	v_mul_f32_e32 v31, 0x3fb8aa3b, v31
	s_lshl_b64 s[42:43], s[80:81], 9
	v_exp_f32_e32 v28, v28
	v_exp_f32_e32 v29, v29
	v_exp_f32_e32 v30, v30
	v_exp_f32_e32 v31, v31
	v_mul_f32_e32 v20, 0x3fb8aa3b, v20
	v_mul_f32_e32 v21, 0x3fb8aa3b, v21
	v_mul_f32_e32 v22, 0x3fb8aa3b, v22
	v_mul_f32_e32 v23, 0x3fb8aa3b, v23
	v_lshl_add_u64 v[36:37], v[54:55], 0, s[42:43]
	v_exp_f32_e32 v20, v20
	v_exp_f32_e32 v21, v21
	v_exp_f32_e32 v22, v22
	v_exp_f32_e32 v23, v23
	global_store_dwordx4 v[36:37], v[32:35], off
	global_store_dwordx4 v[36:37], v[24:27], off offset:16
	global_store_dwordx4 v[36:37], v[28:31], off offset:32
	global_store_dwordx4 v[36:37], v[20:23], off offset:48
